# attention loops: per-tile accumulator-init subtractions (-m - ck) and the 32-term softmax row-sum chains use v_pk_add_f32 (half the VALU instructions); MFMA-result hazard distances kept with s_nop
# baseline (speedup 1.0000x reference)
.LBB0_1339:
	ds_read_b128 v[2:5], v184
	ds_read_b128 v[6:9], v184 offset:32
	ds_read_b128 v[10:13], v184 offset:64
	ds_read_b128 v[80:83], v184 offset:96
	ds_read_b128 v[240:243], v184 offset:128
	ds_read_b128 v[84:87], v184 offset:160
	ds_read_b128 v[88:91], v184 offset:192
	ds_read_b128 v[92:95], v184 offset:224
	s_waitcnt lgkmcnt(4)
	v_pk_add_f32 v[110:111], v[82:83], v[236:237] op_sel:[0,1] op_sel_hi:[1,1] neg_lo:[1,1] neg_hi:[1,1]
	v_pk_add_f32 v[108:109], v[80:81], v[236:237] op_sel:[0,1] op_sel_hi:[1,1] neg_lo:[1,1] neg_hi:[1,1]
	v_pk_add_f32 v[106:107], v[12:13], v[236:237] op_sel:[0,1] op_sel_hi:[1,1] neg_lo:[1,1] neg_hi:[1,1]
	v_pk_add_f32 v[104:105], v[10:11], v[236:237] op_sel:[0,1] op_sel_hi:[1,1] neg_lo:[1,1] neg_hi:[1,1]
	v_pk_add_f32 v[102:103], v[8:9], v[236:237] op_sel:[0,1] op_sel_hi:[1,1] neg_lo:[1,1] neg_hi:[1,1]
	v_pk_add_f32 v[100:101], v[6:7], v[236:237] op_sel:[0,1] op_sel_hi:[1,1] neg_lo:[1,1] neg_hi:[1,1]
	v_pk_add_f32 v[98:99], v[4:5], v[236:237] op_sel:[0,1] op_sel_hi:[1,1] neg_lo:[1,1] neg_hi:[1,1]
	v_pk_add_f32 v[96:97], v[2:3], v[236:237] op_sel:[0,1] op_sel_hi:[1,1] neg_lo:[1,1] neg_hi:[1,1]
	s_waitcnt lgkmcnt(0)
	v_pk_add_f32 v[94:95], v[94:95], v[236:237] op_sel:[0,1] op_sel_hi:[1,1] neg_lo:[1,1] neg_hi:[1,1]
	v_pk_add_f32 v[92:93], v[92:93], v[236:237] op_sel:[0,1] op_sel_hi:[1,1] neg_lo:[1,1] neg_hi:[1,1]
	v_pk_add_f32 v[90:91], v[90:91], v[236:237] op_sel:[0,1] op_sel_hi:[1,1] neg_lo:[1,1] neg_hi:[1,1]
	v_pk_add_f32 v[88:89], v[88:89], v[236:237] op_sel:[0,1] op_sel_hi:[1,1] neg_lo:[1,1] neg_hi:[1,1]
	v_pk_add_f32 v[86:87], v[86:87], v[236:237] op_sel:[0,1] op_sel_hi:[1,1] neg_lo:[1,1] neg_hi:[1,1]
	v_pk_add_f32 v[84:85], v[84:85], v[236:237] op_sel:[0,1] op_sel_hi:[1,1] neg_lo:[1,1] neg_hi:[1,1]
	v_pk_add_f32 v[82:83], v[242:243], v[236:237] op_sel:[0,1] op_sel_hi:[1,1] neg_lo:[1,1] neg_hi:[1,1]
	v_pk_add_f32 v[80:81], v[240:241], v[236:237] op_sel:[0,1] op_sel_hi:[1,1] neg_lo:[1,1] neg_hi:[1,1]
	v_add_u32_e32 v0, s40, v236
	ds_read_b64_tr_b16 v[2:3], v0 offset:24576
	ds_read_b64_tr_b16 v[4:5], v0 offset:25088
	v_mfma_f32_32x32x16_bf16 v[96:111], v[172:175], v[124:127], v[96:111]
	v_pk_add_f32 v[244:245], v[64:65], v[66:67]
	v_pk_add_f32 v[244:245], v[68:69], v[244:245]
	v_cvt_pk_bf16_f32 v140, v64, v65
	v_cvt_pk_bf16_f32 v141, v66, v67
	ds_read_b64_tr_b16 v[6:7], v0 offset:28672
	ds_read_b64_tr_b16 v[8:9], v0 offset:29184
	v_mfma_f32_32x32x16_bf16 v[80:95], v[168:171], v[124:127], v[80:95]
	v_pk_add_f32 v[244:245], v[70:71], v[244:245]
	v_pk_add_f32 v[244:245], v[72:73], v[244:245]
	v_cvt_pk_bf16_f32 v142, v68, v69
	v_cvt_pk_bf16_f32 v143, v70, v71
	ds_read_b64_tr_b16 v[10:11], v0 offset:25600
	ds_read_b64_tr_b16 v[12:13], v0 offset:26112
	v_mfma_f32_32x32x16_bf16 v[96:111], v[164:167], v[120:123], v[96:111]
	v_pk_add_f32 v[244:245], v[74:75], v[244:245]
	v_pk_add_f32 v[244:245], v[76:77], v[244:245]
	v_cvt_pk_bf16_f32 v136, v72, v73
	v_cvt_pk_bf16_f32 v137, v74, v75
	ds_read_b64_tr_b16 v[64:65], v0 offset:29696
	ds_read_b64_tr_b16 v[66:67], v0 offset:30208
	v_mfma_f32_32x32x16_bf16 v[80:95], v[160:163], v[120:123], v[80:95]
	v_pk_add_f32 v[244:245], v[78:79], v[244:245]
	v_pk_add_f32 v[244:245], v[48:49], v[244:245]
	v_cvt_pk_bf16_f32 v138, v76, v77
	v_cvt_pk_bf16_f32 v139, v78, v79
	ds_read_b64_tr_b16 v[68:69], v0 offset:26624
	ds_read_b64_tr_b16 v[70:71], v0 offset:27136
	v_mfma_f32_32x32x16_bf16 v[96:111], v[156:159], v[116:119], v[96:111]
	v_pk_add_f32 v[244:245], v[50:51], v[244:245]
	v_pk_add_f32 v[244:245], v[52:53], v[244:245]
	v_cvt_pk_bf16_f32 v132, v48, v49
	v_cvt_pk_bf16_f32 v133, v50, v51
	ds_read_b64_tr_b16 v[48:49], v0 offset:30720
	ds_read_b64_tr_b16 v[50:51], v0 offset:31232
	v_mfma_f32_32x32x16_bf16 v[80:95], v[152:155], v[116:119], v[80:95]
	v_pk_add_f32 v[244:245], v[54:55], v[244:245]
	v_pk_add_f32 v[244:245], v[56:57], v[244:245]
	v_cvt_pk_bf16_f32 v134, v52, v53
	v_cvt_pk_bf16_f32 v135, v54, v55
	ds_read_b64_tr_b16 v[52:53], v0 offset:27648
	ds_read_b64_tr_b16 v[54:55], v0 offset:28160
	v_mfma_f32_32x32x16_bf16 v[96:111], v[148:151], v[112:115], v[96:111]
	v_pk_add_f32 v[244:245], v[58:59], v[244:245]
	s_nop 0
	v_pk_add_f32 v[244:245], v[60:61], v[244:245]
	s_nop 0
	v_cvt_pk_bf16_f32 v128, v56, v57
	v_cvt_pk_bf16_f32 v129, v58, v59
	ds_read_b64_tr_b16 v[56:57], v0 offset:31744
	ds_read_b64_tr_b16 v[58:59], v0 offset:32256
	v_mfma_f32_32x32x16_bf16 v[80:95], v[144:147], v[112:115], v[80:95]
	v_pk_add_f32 v[244:245], v[62:63], v[244:245]
	s_nop 0
	v_add_f32_e32 v0, v244, v245
	v_cvt_pk_bf16_f32 v130, v60, v61
	v_cvt_pk_bf16_f32 v131, v62, v63
	v_lshl_add_u64 v[14:15], v[182:183], 0, s[86:87]
	s_add_i32 s8, s49, s5
	s_mov_b32 s9, m0
	s_mov_b32 m0, s8
	s_nop 0
	global_load_lds_dwordx4 v[14:15], off
	s_mov_b32 m0, s9
	v_lshl_add_u64 v[14:15], v[180:181], 0, s[86:87]
	s_add_i32 s8, s48, s56
	s_mov_b32 s9, m0
	s_mov_b32 m0, s8
	s_nop 0
	global_load_lds_dwordx4 v[14:15], off
	s_mov_b32 m0, s9
	v_max_f32_e32 v14, v97, v97
	v_max_f32_e32 v15, v96, v96
	v_max_f32_e32 v14, v15, v14
	v_max3_f32 v15, v98, v99, v81
	v_max3_f32 v14, v14, v80, v82
	v_max3_f32 v14, v14, v83, v100
	v_max3_f32 v15, v15, v102, v103
	v_max3_f32 v14, v14, v101, v84
	v_max3_f32 v15, v15, v86, v87
	v_max3_f32 v14, v14, v85, v104
	v_max3_f32 v15, v15, v106, v107
	v_max3_f32 v14, v14, v105, v88
	v_max3_f32 v15, v15, v90, v91
	v_max3_f32 v14, v14, v89, v108
	v_max3_f32 v15, v15, v110, v111
	v_max3_f32 v14, v14, v109, v92
	v_max3_f32 v15, v15, v94, v95
	v_max3_f32 v14, v14, v93, v15
	v_mov_b32_e32 v15, v14
	s_nop 1
	v_permlane32_swap_b32_e32 v14, v15
	v_max_f32_e32 v15, v15, v15
	v_max_f32_e32 v14, v14, v14
	v_max_f32_e32 v14, v14, v15
	v_cmp_lt_f32_e32 vcc, s93, v14
	s_cmp_lg_u64 vcc, 0
	v_add_f32_e32 v0, v238, v0
	s_cselect_b64 s[40:41], -1, 0
	s_cbranch_vccnz .LBB0_1347

.LBB0_1342:
	s_add_i32 s8, s48, 0x2000
	ds_read_b128 v[48:51], v184 offset:256
	ds_read_b128 v[52:55], v184 offset:288
	ds_read_b128 v[56:59], v184 offset:320
	ds_read_b128 v[60:63], v184 offset:352
	ds_read_b128 v[152:155], v184 offset:384
	ds_read_b128 v[168:171], v184 offset:416
	ds_read_b128 v[172:175], v184 offset:448
	ds_read_b128 v[238:241], v184 offset:480
	s_cmpk_lg_i32 s48, 0x4000
	s_waitcnt lgkmcnt(4)
	v_pk_add_f32 v[78:79], v[62:63], v[236:237] op_sel:[0,1] op_sel_hi:[1,1] neg_lo:[1,1] neg_hi:[1,1]
	v_pk_add_f32 v[76:77], v[60:61], v[236:237] op_sel:[0,1] op_sel_hi:[1,1] neg_lo:[1,1] neg_hi:[1,1]
	v_pk_add_f32 v[74:75], v[58:59], v[236:237] op_sel:[0,1] op_sel_hi:[1,1] neg_lo:[1,1] neg_hi:[1,1]
	v_pk_add_f32 v[72:73], v[56:57], v[236:237] op_sel:[0,1] op_sel_hi:[1,1] neg_lo:[1,1] neg_hi:[1,1]
	v_pk_add_f32 v[70:71], v[54:55], v[236:237] op_sel:[0,1] op_sel_hi:[1,1] neg_lo:[1,1] neg_hi:[1,1]
	v_pk_add_f32 v[68:69], v[52:53], v[236:237] op_sel:[0,1] op_sel_hi:[1,1] neg_lo:[1,1] neg_hi:[1,1]
	v_pk_add_f32 v[66:67], v[50:51], v[236:237] op_sel:[0,1] op_sel_hi:[1,1] neg_lo:[1,1] neg_hi:[1,1]
	v_pk_add_f32 v[64:65], v[48:49], v[236:237] op_sel:[0,1] op_sel_hi:[1,1] neg_lo:[1,1] neg_hi:[1,1]
	s_waitcnt lgkmcnt(0)
	v_pk_add_f32 v[62:63], v[240:241], v[236:237] op_sel:[0,1] op_sel_hi:[1,1] neg_lo:[1,1] neg_hi:[1,1]
	v_pk_add_f32 v[60:61], v[238:239], v[236:237] op_sel:[0,1] op_sel_hi:[1,1] neg_lo:[1,1] neg_hi:[1,1]
	v_pk_add_f32 v[58:59], v[174:175], v[236:237] op_sel:[0,1] op_sel_hi:[1,1] neg_lo:[1,1] neg_hi:[1,1]
	v_pk_add_f32 v[56:57], v[172:173], v[236:237] op_sel:[0,1] op_sel_hi:[1,1] neg_lo:[1,1] neg_hi:[1,1]
	v_pk_add_f32 v[54:55], v[170:171], v[236:237] op_sel:[0,1] op_sel_hi:[1,1] neg_lo:[1,1] neg_hi:[1,1]
	v_pk_add_f32 v[52:53], v[168:169], v[236:237] op_sel:[0,1] op_sel_hi:[1,1] neg_lo:[1,1] neg_hi:[1,1]
	v_pk_add_f32 v[50:51], v[154:155], v[236:237] op_sel:[0,1] op_sel_hi:[1,1] neg_lo:[1,1] neg_hi:[1,1]
	v_pk_add_f32 v[48:49], v[152:153], v[236:237] op_sel:[0,1] op_sel_hi:[1,1] neg_lo:[1,1] neg_hi:[1,1]
	s_cselect_b32 s57, s8, 0
	v_add_u32_e32 v14, s49, v236
	ds_read_b64_tr_b16 v[152:153], v14 offset:24576
	ds_read_b64_tr_b16 v[154:155], v14 offset:25088
	v_mfma_f32_32x32x16_bf16 v[64:79], v[164:167], v[124:127], v[64:79]
	v_pk_add_f32 v[246:247], v[96:97], v[98:99]
	v_pk_add_f32 v[246:247], v[100:101], v[246:247]
	v_cvt_pk_bf16_f32 v140, v96, v97
	v_cvt_pk_bf16_f32 v141, v98, v99
	ds_read_b64_tr_b16 v[96:97], v14 offset:28672
	ds_read_b64_tr_b16 v[98:99], v14 offset:29184
	v_mfma_f32_32x32x16_bf16 v[48:63], v[160:163], v[124:127], v[48:63]
	v_pk_add_f32 v[246:247], v[102:103], v[246:247]
	v_pk_add_f32 v[246:247], v[104:105], v[246:247]
	v_cvt_pk_bf16_f32 v142, v100, v101
	v_cvt_pk_bf16_f32 v143, v102, v103
	ds_read_b64_tr_b16 v[100:101], v14 offset:25600
	ds_read_b64_tr_b16 v[102:103], v14 offset:26112
	v_mfma_f32_32x32x16_bf16 v[64:79], v[156:159], v[120:123], v[64:79]
	v_pk_add_f32 v[246:247], v[106:107], v[246:247]
	v_pk_add_f32 v[246:247], v[108:109], v[246:247]
	v_cvt_pk_bf16_f32 v136, v104, v105
	v_cvt_pk_bf16_f32 v137, v106, v107
	ds_read_b64_tr_b16 v[104:105], v14 offset:29696
	ds_read_b64_tr_b16 v[106:107], v14 offset:30208
	v_mfma_f32_32x32x16_bf16 v[48:63], v[148:151], v[120:123], v[48:63]
	v_pk_add_f32 v[246:247], v[110:111], v[246:247]
	v_pk_add_f32 v[246:247], v[80:81], v[246:247]
	v_cvt_pk_bf16_f32 v138, v108, v109
	v_cvt_pk_bf16_f32 v139, v110, v111
	ds_read_b64_tr_b16 v[108:109], v14 offset:26624
	ds_read_b64_tr_b16 v[110:111], v14 offset:27136
	v_mfma_f32_32x32x16_bf16 v[64:79], v[144:147], v[116:119], v[64:79]
	v_pk_add_f32 v[246:247], v[82:83], v[246:247]
	v_pk_add_f32 v[246:247], v[84:85], v[246:247]
	v_cvt_pk_bf16_f32 v132, v80, v81
	v_cvt_pk_bf16_f32 v133, v82, v83
	ds_read_b64_tr_b16 v[80:81], v14 offset:30720
	ds_read_b64_tr_b16 v[82:83], v14 offset:31232
	v_mfma_f32_32x32x16_bf16 v[48:63], v[10:13], v[116:119], v[48:63]
	v_pk_add_f32 v[246:247], v[86:87], v[246:247]
	v_pk_add_f32 v[246:247], v[88:89], v[246:247]
	v_cvt_pk_bf16_f32 v134, v84, v85
	v_cvt_pk_bf16_f32 v135, v86, v87
	ds_read_b64_tr_b16 v[10:11], v14 offset:27648
	ds_read_b64_tr_b16 v[12:13], v14 offset:28160
	v_mfma_f32_32x32x16_bf16 v[64:79], v[6:9], v[112:115], v[64:79]
	v_pk_add_f32 v[246:247], v[90:91], v[246:247]
	s_nop 0
	v_pk_add_f32 v[246:247], v[92:93], v[246:247]
	s_nop 0
	v_cvt_pk_bf16_f32 v128, v88, v89
	v_cvt_pk_bf16_f32 v129, v90, v91
	ds_read_b64_tr_b16 v[6:7], v14 offset:31744
	ds_read_b64_tr_b16 v[8:9], v14 offset:32256
	v_mfma_f32_32x32x16_bf16 v[48:63], v[2:5], v[112:115], v[48:63]
	v_pk_add_f32 v[246:247], v[94:95], v[246:247]
	s_nop 0
	v_add_f32_e32 v2, v246, v247
	v_cvt_pk_bf16_f32 v130, v92, v93
	v_cvt_pk_bf16_f32 v131, v94, v95
	v_max_f32_e32 v3, v65, v65
	v_max_f32_e32 v4, v64, v64
	v_max_f32_e32 v3, v4, v3
	s_nop 3
	v_max3_f32 v4, v66, v67, v49
	v_max3_f32 v3, v3, v48, v50
	v_max3_f32 v3, v3, v51, v68
	v_max3_f32 v4, v4, v70, v71
	v_max3_f32 v3, v3, v69, v52
	v_max3_f32 v4, v4, v54, v55
	v_max3_f32 v3, v3, v53, v72
	v_max3_f32 v4, v4, v74, v75
	v_max3_f32 v3, v3, v73, v56
	v_max3_f32 v4, v4, v58, v59
	v_max3_f32 v3, v3, v57, v76
	v_max3_f32 v4, v4, v78, v79
	v_max3_f32 v3, v3, v77, v60
	v_max3_f32 v4, v4, v62, v63
	v_add_f32_e32 v238, v0, v2
	v_max3_f32 v0, v3, v61, v4
	v_mov_b32_e32 v2, v0
	s_nop 1
	v_permlane32_swap_b32_e32 v0, v2
	v_max_f32_e32 v2, v2, v2
	v_max_f32_e32 v0, v0, v0
	s_add_i32 s8, s48, s5
	s_mov_b32 s9, m0
	s_mov_b32 m0, s8
	s_nop 0
	global_load_lds_dwordx4 v[182:183], off
	s_mov_b32 m0, s9
	v_max_f32_e32 v0, v0, v2
	s_add_i32 s8, s57, s56
	s_mov_b32 s9, m0
	s_mov_b32 m0, s8
	s_nop 0
	global_load_lds_dwordx4 v[180:181], off
	s_mov_b32 m0, s9
	v_cmp_lt_f32_e32 vcc, s93, v0
	s_cmp_lg_u64 vcc, 0
	s_cselect_b64 s[40:41], -1, 0
	s_cbranch_vccnz .LBB0_1350

.LBB0_1362:
	s_lshl_b32 s4, s4, 8
	s_add_i32 s4, s4, 0
	s_add_i32 s4, s4, 0x15000
	v_lshl_add_u32 v0, v229, 2, s4
	v_add_u32_e32 v0, 0xffffff00, v0
	ds_read_b128 v[2:5], v0
	ds_read_b128 v[6:9], v0 offset:32
	ds_read_b128 v[10:13], v0 offset:64
	ds_read_b128 v[80:83], v0 offset:96
	ds_read_b128 v[96:99], v0 offset:128
	ds_read_b128 v[100:103], v0 offset:160
	ds_read_b128 v[104:107], v0 offset:192
	ds_read_b128 v[108:111], v0 offset:224
	v_add_u32_e32 v0, s58, v236
	s_waitcnt lgkmcnt(4)
	v_pk_add_f32 v[94:95], v[82:83], v[236:237] op_sel:[0,1] op_sel_hi:[1,1] neg_lo:[1,1] neg_hi:[1,1]
	v_pk_add_f32 v[92:93], v[80:81], v[236:237] op_sel:[0,1] op_sel_hi:[1,1] neg_lo:[1,1] neg_hi:[1,1]
	v_pk_add_f32 v[90:91], v[12:13], v[236:237] op_sel:[0,1] op_sel_hi:[1,1] neg_lo:[1,1] neg_hi:[1,1]
	v_pk_add_f32 v[88:89], v[10:11], v[236:237] op_sel:[0,1] op_sel_hi:[1,1] neg_lo:[1,1] neg_hi:[1,1]
	v_pk_add_f32 v[86:87], v[8:9], v[236:237] op_sel:[0,1] op_sel_hi:[1,1] neg_lo:[1,1] neg_hi:[1,1]
	v_pk_add_f32 v[84:85], v[6:7], v[236:237] op_sel:[0,1] op_sel_hi:[1,1] neg_lo:[1,1] neg_hi:[1,1]
	v_pk_add_f32 v[82:83], v[4:5], v[236:237] op_sel:[0,1] op_sel_hi:[1,1] neg_lo:[1,1] neg_hi:[1,1]
	v_pk_add_f32 v[80:81], v[2:3], v[236:237] op_sel:[0,1] op_sel_hi:[1,1] neg_lo:[1,1] neg_hi:[1,1]
	s_waitcnt lgkmcnt(0)
	v_pk_add_f32 v[110:111], v[110:111], v[236:237] op_sel:[0,1] op_sel_hi:[1,1] neg_lo:[1,1] neg_hi:[1,1]
	v_pk_add_f32 v[108:109], v[108:109], v[236:237] op_sel:[0,1] op_sel_hi:[1,1] neg_lo:[1,1] neg_hi:[1,1]
	v_pk_add_f32 v[106:107], v[106:107], v[236:237] op_sel:[0,1] op_sel_hi:[1,1] neg_lo:[1,1] neg_hi:[1,1]
	v_pk_add_f32 v[104:105], v[104:105], v[236:237] op_sel:[0,1] op_sel_hi:[1,1] neg_lo:[1,1] neg_hi:[1,1]
	v_pk_add_f32 v[102:103], v[102:103], v[236:237] op_sel:[0,1] op_sel_hi:[1,1] neg_lo:[1,1] neg_hi:[1,1]
	v_pk_add_f32 v[100:101], v[100:101], v[236:237] op_sel:[0,1] op_sel_hi:[1,1] neg_lo:[1,1] neg_hi:[1,1]
	v_pk_add_f32 v[98:99], v[98:99], v[236:237] op_sel:[0,1] op_sel_hi:[1,1] neg_lo:[1,1] neg_hi:[1,1]
	v_pk_add_f32 v[96:97], v[96:97], v[236:237] op_sel:[0,1] op_sel_hi:[1,1] neg_lo:[1,1] neg_hi:[1,1]
	ds_read_b64_tr_b16 v[2:3], v0 offset:24576
	ds_read_b64_tr_b16 v[4:5], v0 offset:25088
	v_pk_add_f32 v[248:249], v[64:65], v[66:67]
	v_pk_add_f32 v[248:249], v[68:69], v[248:249]
	v_cvt_pk_bf16_f32 v140, v64, v65
	v_cvt_pk_bf16_f32 v141, v66, v67
	v_mfma_f32_32x32x16_bf16 v[80:95], v[172:175], v[124:127], v[80:95]
	ds_read_b64_tr_b16 v[6:7], v0 offset:28672
	ds_read_b64_tr_b16 v[8:9], v0 offset:29184
	v_pk_add_f32 v[248:249], v[70:71], v[248:249]
	v_pk_add_f32 v[248:249], v[72:73], v[248:249]
	v_cvt_pk_bf16_f32 v142, v68, v69
	v_cvt_pk_bf16_f32 v143, v70, v71
	v_mfma_f32_32x32x16_bf16 v[96:111], v[168:171], v[124:127], v[96:111]
	ds_read_b64_tr_b16 v[10:11], v0 offset:25600
	ds_read_b64_tr_b16 v[12:13], v0 offset:26112
	v_pk_add_f32 v[248:249], v[74:75], v[248:249]
	v_pk_add_f32 v[248:249], v[76:77], v[248:249]
	v_cvt_pk_bf16_f32 v136, v72, v73
	v_cvt_pk_bf16_f32 v137, v74, v75
	v_mfma_f32_32x32x16_bf16 v[80:95], v[164:167], v[120:123], v[80:95]
	ds_read_b64_tr_b16 v[124:125], v0 offset:29696
	ds_read_b64_tr_b16 v[126:127], v0 offset:30208
	v_pk_add_f32 v[248:249], v[78:79], v[248:249]
	v_pk_add_f32 v[248:249], v[48:49], v[248:249]
	v_cvt_pk_bf16_f32 v138, v76, v77
	v_cvt_pk_bf16_f32 v139, v78, v79
	v_mfma_f32_32x32x16_bf16 v[96:111], v[160:163], v[120:123], v[96:111]
	ds_read_b64_tr_b16 v[120:121], v0 offset:26624
	ds_read_b64_tr_b16 v[122:123], v0 offset:27136
	v_pk_add_f32 v[248:249], v[50:51], v[248:249]
	v_pk_add_f32 v[248:249], v[52:53], v[248:249]
	v_cvt_pk_bf16_f32 v132, v48, v49
	v_cvt_pk_bf16_f32 v133, v50, v51
	v_mfma_f32_32x32x16_bf16 v[80:95], v[156:159], v[116:119], v[80:95]
	ds_read_b64_tr_b16 v[156:157], v0 offset:30720
	ds_read_b64_tr_b16 v[158:159], v0 offset:31232
	v_pk_add_f32 v[248:249], v[54:55], v[248:249]
	v_pk_add_f32 v[248:249], v[56:57], v[248:249]
	v_cvt_pk_bf16_f32 v134, v52, v53
	v_cvt_pk_bf16_f32 v135, v54, v55
	v_mfma_f32_32x32x16_bf16 v[96:111], v[152:155], v[116:119], v[96:111]
	ds_read_b64_tr_b16 v[116:117], v0 offset:27648
	ds_read_b64_tr_b16 v[118:119], v0 offset:28160
	v_pk_add_f32 v[248:249], v[58:59], v[248:249]
	s_nop 0
	v_pk_add_f32 v[248:249], v[60:61], v[248:249]
	s_nop 0
	v_cvt_pk_bf16_f32 v128, v56, v57
	v_cvt_pk_bf16_f32 v129, v58, v59
	v_mfma_f32_32x32x16_bf16 v[80:95], v[148:151], v[112:115], v[80:95]
	ds_read_b64_tr_b16 v[148:149], v0 offset:31744
	ds_read_b64_tr_b16 v[150:151], v0 offset:32256
	v_pk_add_f32 v[248:249], v[62:63], v[248:249]
	s_nop 0
	v_add_f32_e32 v0, v248, v249
	v_cvt_pk_bf16_f32 v130, v60, v61
	v_cvt_pk_bf16_f32 v131, v62, v63
	v_mfma_f32_32x32x16_bf16 v[96:111], v[144:147], v[112:115], v[96:111]
	v_or_b32_e32 v15, 0xe0, v229
	v_or_b32_e32 v14, 0xc0, v229
	v_cmp_le_i32_e32 vcc, v15, v234
	v_add_f32_e32 v0, v238, v0
	s_nop 7
	v_cndmask_b32_e32 v48, v223, v96, vcc
	v_cmp_lt_i32_e32 vcc, v14, v234
	s_nop 1
	v_cndmask_b32_e32 v65, v223, v81, vcc
	v_cmp_le_i32_e32 vcc, v14, v234
	v_or_b32_e32 v14, 0xe1, v229
	s_nop 0
	v_cndmask_b32_e32 v64, v223, v80, vcc
	v_cmp_le_i32_e32 vcc, v14, v234
	v_or_b32_e32 v14, 0xc2, v229
	v_max_f32_e32 v15, v64, v64
	v_cndmask_b32_e32 v49, v223, v97, vcc
	v_cmp_le_i32_e32 vcc, v14, v234
	v_or_b32_e32 v14, 0xe2, v229
	s_nop 0
	v_cndmask_b32_e32 v66, v223, v82, vcc
	v_cmp_le_i32_e32 vcc, v14, v234
	v_or_b32_e32 v14, 0xc3, v229
	s_nop 0
	v_cndmask_b32_e32 v50, v223, v98, vcc
	v_cmp_le_i32_e32 vcc, v14, v234
	v_or_b32_e32 v14, 0xe3, v229
	s_nop 0
	v_cndmask_b32_e32 v67, v223, v83, vcc
	v_cmp_le_i32_e32 vcc, v14, v234
	v_or_b32_e32 v14, 0xc8, v229
	s_nop 0
	v_cndmask_b32_e32 v51, v223, v99, vcc
	v_cmp_le_i32_e32 vcc, v14, v234
	v_or_b32_e32 v14, 0xe8, v229
	s_nop 0
	v_cndmask_b32_e32 v68, v223, v84, vcc
	v_cmp_le_i32_e32 vcc, v14, v234
	v_or_b32_e32 v14, 0xc9, v229
	s_nop 0
	v_cndmask_b32_e32 v52, v223, v100, vcc
	v_cmp_le_i32_e32 vcc, v14, v234
	v_or_b32_e32 v14, 0xe9, v229
	s_nop 0
	v_cndmask_b32_e32 v69, v223, v85, vcc
	v_cmp_le_i32_e32 vcc, v14, v234
	v_or_b32_e32 v14, 0xca, v229
	s_nop 0
	v_cndmask_b32_e32 v53, v223, v101, vcc
	v_cmp_le_i32_e32 vcc, v14, v234
	v_or_b32_e32 v14, 0xea, v229
	s_nop 0
	v_cndmask_b32_e32 v70, v223, v86, vcc
	v_cmp_le_i32_e32 vcc, v14, v234
	v_or_b32_e32 v14, 0xcb, v229
	s_nop 0
	v_cndmask_b32_e32 v54, v223, v102, vcc
	v_cmp_le_i32_e32 vcc, v14, v234
	v_or_b32_e32 v14, 0xeb, v229
	s_nop 0
	v_cndmask_b32_e32 v71, v223, v87, vcc
	v_cmp_le_i32_e32 vcc, v14, v234
	v_or_b32_e32 v14, 0xd0, v229
	s_nop 0
	v_cndmask_b32_e32 v55, v223, v103, vcc
	v_cmp_le_i32_e32 vcc, v14, v234
	v_or_b32_e32 v14, 0xf0, v229
	s_nop 0
	v_cndmask_b32_e32 v72, v223, v88, vcc
	v_cmp_le_i32_e32 vcc, v14, v234
	v_or_b32_e32 v14, 0xd1, v229
	s_nop 0
	v_cndmask_b32_e32 v56, v223, v104, vcc
	v_cmp_le_i32_e32 vcc, v14, v234
	v_or_b32_e32 v14, 0xf1, v229
	s_nop 0
	v_cndmask_b32_e32 v73, v223, v89, vcc
	v_cmp_le_i32_e32 vcc, v14, v234
	v_or_b32_e32 v14, 0xd2, v229
	s_nop 0
	v_cndmask_b32_e32 v57, v223, v105, vcc
	v_cmp_le_i32_e32 vcc, v14, v234
	v_or_b32_e32 v14, 0xf2, v229
	s_nop 0
	v_cndmask_b32_e32 v74, v223, v90, vcc
	v_cmp_le_i32_e32 vcc, v14, v234
	v_or_b32_e32 v14, 0xd3, v229
	s_nop 0
	v_cndmask_b32_e32 v58, v223, v106, vcc
	v_cmp_le_i32_e32 vcc, v14, v234
	v_or_b32_e32 v14, 0xf3, v229
	s_nop 0
	v_cndmask_b32_e32 v75, v223, v91, vcc
	v_cmp_le_i32_e32 vcc, v14, v234
	v_or_b32_e32 v14, 0xd8, v229
	s_nop 0
	v_cndmask_b32_e32 v59, v223, v107, vcc
	v_cmp_le_i32_e32 vcc, v14, v234
	v_or_b32_e32 v14, 0xf8, v229
	s_nop 0
	v_cndmask_b32_e32 v76, v223, v92, vcc
	v_cmp_le_i32_e32 vcc, v14, v234
	v_or_b32_e32 v14, 0xd9, v229
	s_nop 0
	v_cndmask_b32_e32 v60, v223, v108, vcc
	v_cmp_le_i32_e32 vcc, v14, v234
	v_or_b32_e32 v14, 0xf9, v229
	s_nop 0
	v_cndmask_b32_e32 v77, v223, v93, vcc
	v_cmp_le_i32_e32 vcc, v14, v234
	v_or_b32_e32 v14, 0xda, v229
	s_nop 0
	v_cndmask_b32_e32 v61, v223, v109, vcc
	v_cmp_le_i32_e32 vcc, v14, v234
	v_or_b32_e32 v14, 0xfa, v229
	s_nop 0
	v_cndmask_b32_e32 v78, v223, v94, vcc
	v_cmp_le_i32_e32 vcc, v14, v234
	v_or_b32_e32 v14, 0xdb, v229
	s_nop 0
	v_cndmask_b32_e32 v62, v223, v110, vcc
	v_cmp_le_i32_e32 vcc, v14, v234
	v_or_b32_e32 v14, 0xfb, v229
	s_nop 0
	v_cndmask_b32_e32 v79, v223, v95, vcc
	v_cmp_le_i32_e32 vcc, v14, v234
	v_max_f32_e32 v14, v65, v65
	v_max_f32_e32 v14, v15, v14
	v_max3_f32 v15, v66, v67, v49
	v_max3_f32 v14, v14, v48, v50
	v_max3_f32 v14, v14, v51, v68
	v_max3_f32 v15, v15, v70, v71
	v_max3_f32 v14, v14, v69, v52
	v_max3_f32 v15, v15, v54, v55
	v_max3_f32 v14, v14, v53, v72
	v_max3_f32 v15, v15, v74, v75
	v_max3_f32 v14, v14, v73, v56
	v_max3_f32 v15, v15, v58, v59
	v_cndmask_b32_e32 v63, v223, v111, vcc
	v_max3_f32 v14, v14, v57, v76
	v_max3_f32 v15, v15, v78, v79
	v_max3_f32 v14, v14, v77, v60
	v_max3_f32 v15, v15, v62, v63
	v_max3_f32 v14, v14, v61, v15
	v_mov_b32_e32 v15, v14
	s_nop 1
	v_permlane32_swap_b32_e32 v14, v15
	v_max_f32_e32 v15, v15, v15
	v_max_f32_e32 v14, v14, v14
	v_max_f32_e32 v14, v14, v15
	v_cmp_lt_f32_e32 vcc, s93, v14
	s_cmp_lg_u64 vcc, 0
	s_cselect_b64 s[38:39], -1, 0
	s_cbranch_vccnz .LBB0_1466

.LBB0_1374:
	ds_read_b128 v[2:5], v239
	ds_read_b128 v[6:9], v239 offset:32
	ds_read_b128 v[10:13], v239 offset:64
	ds_read_b128 v[80:83], v239 offset:96
	ds_read_b128 v[176:179], v239 offset:128
	ds_read_b128 v[84:87], v239 offset:160
	ds_read_b128 v[88:91], v239 offset:192
	ds_read_b128 v[92:95], v239 offset:224
	s_waitcnt lgkmcnt(4)
	v_pk_add_f32 v[110:111], v[82:83], v[236:237] op_sel:[0,1] op_sel_hi:[1,1] neg_lo:[1,1] neg_hi:[1,1]
	v_pk_add_f32 v[108:109], v[80:81], v[236:237] op_sel:[0,1] op_sel_hi:[1,1] neg_lo:[1,1] neg_hi:[1,1]
	v_pk_add_f32 v[106:107], v[12:13], v[236:237] op_sel:[0,1] op_sel_hi:[1,1] neg_lo:[1,1] neg_hi:[1,1]
	v_pk_add_f32 v[104:105], v[10:11], v[236:237] op_sel:[0,1] op_sel_hi:[1,1] neg_lo:[1,1] neg_hi:[1,1]
	v_pk_add_f32 v[102:103], v[8:9], v[236:237] op_sel:[0,1] op_sel_hi:[1,1] neg_lo:[1,1] neg_hi:[1,1]
	v_pk_add_f32 v[100:101], v[6:7], v[236:237] op_sel:[0,1] op_sel_hi:[1,1] neg_lo:[1,1] neg_hi:[1,1]
	v_pk_add_f32 v[98:99], v[4:5], v[236:237] op_sel:[0,1] op_sel_hi:[1,1] neg_lo:[1,1] neg_hi:[1,1]
	v_pk_add_f32 v[96:97], v[2:3], v[236:237] op_sel:[0,1] op_sel_hi:[1,1] neg_lo:[1,1] neg_hi:[1,1]
	s_waitcnt lgkmcnt(0)
	v_pk_add_f32 v[94:95], v[94:95], v[236:237] op_sel:[0,1] op_sel_hi:[1,1] neg_lo:[1,1] neg_hi:[1,1]
	v_pk_add_f32 v[92:93], v[92:93], v[236:237] op_sel:[0,1] op_sel_hi:[1,1] neg_lo:[1,1] neg_hi:[1,1]
	v_pk_add_f32 v[90:91], v[90:91], v[236:237] op_sel:[0,1] op_sel_hi:[1,1] neg_lo:[1,1] neg_hi:[1,1]
	v_pk_add_f32 v[88:89], v[88:89], v[236:237] op_sel:[0,1] op_sel_hi:[1,1] neg_lo:[1,1] neg_hi:[1,1]
	v_pk_add_f32 v[86:87], v[86:87], v[236:237] op_sel:[0,1] op_sel_hi:[1,1] neg_lo:[1,1] neg_hi:[1,1]
	v_pk_add_f32 v[84:85], v[84:85], v[236:237] op_sel:[0,1] op_sel_hi:[1,1] neg_lo:[1,1] neg_hi:[1,1]
	v_pk_add_f32 v[82:83], v[178:179], v[236:237] op_sel:[0,1] op_sel_hi:[1,1] neg_lo:[1,1] neg_hi:[1,1]
	v_pk_add_f32 v[80:81], v[176:177], v[236:237] op_sel:[0,1] op_sel_hi:[1,1] neg_lo:[1,1] neg_hi:[1,1]
	v_add_u32_e32 v176, s48, v236
	ds_read_b64_tr_b16 v[2:3], v176 offset:24576
	ds_read_b64_tr_b16 v[4:5], v176 offset:25088
	v_mfma_f32_32x32x16_bf16 v[96:111], v[172:175], v[124:127], v[96:111]
	v_pk_add_f32 v[250:251], v[64:65], v[66:67]
	v_pk_add_f32 v[250:251], v[68:69], v[250:251]
	v_cvt_pk_bf16_f32 v140, v64, v65
	v_cvt_pk_bf16_f32 v141, v66, v67
	ds_read_b64_tr_b16 v[6:7], v176 offset:28672
	ds_read_b64_tr_b16 v[8:9], v176 offset:29184
	v_mfma_f32_32x32x16_bf16 v[80:95], v[168:171], v[124:127], v[80:95]
	v_pk_add_f32 v[250:251], v[70:71], v[250:251]
	v_pk_add_f32 v[250:251], v[72:73], v[250:251]
	v_cvt_pk_bf16_f32 v142, v68, v69
	v_cvt_pk_bf16_f32 v143, v70, v71
	ds_read_b64_tr_b16 v[10:11], v176 offset:25600
	ds_read_b64_tr_b16 v[12:13], v176 offset:26112
	v_mfma_f32_32x32x16_bf16 v[96:111], v[164:167], v[120:123], v[96:111]
	v_pk_add_f32 v[250:251], v[74:75], v[250:251]
	v_pk_add_f32 v[250:251], v[76:77], v[250:251]
	v_cvt_pk_bf16_f32 v136, v72, v73
	v_cvt_pk_bf16_f32 v137, v74, v75
	ds_read_b64_tr_b16 v[64:65], v176 offset:29696
	ds_read_b64_tr_b16 v[66:67], v176 offset:30208
	v_mfma_f32_32x32x16_bf16 v[80:95], v[160:163], v[120:123], v[80:95]
	v_pk_add_f32 v[250:251], v[78:79], v[250:251]
	v_pk_add_f32 v[250:251], v[48:49], v[250:251]
	v_cvt_pk_bf16_f32 v138, v76, v77
	v_cvt_pk_bf16_f32 v139, v78, v79
	ds_read_b64_tr_b16 v[68:69], v176 offset:26624
	ds_read_b64_tr_b16 v[70:71], v176 offset:27136
	v_mfma_f32_32x32x16_bf16 v[96:111], v[156:159], v[116:119], v[96:111]
	v_pk_add_f32 v[250:251], v[50:51], v[250:251]
	v_pk_add_f32 v[250:251], v[52:53], v[250:251]
	v_cvt_pk_bf16_f32 v132, v48, v49
	v_cvt_pk_bf16_f32 v133, v50, v51
	ds_read_b64_tr_b16 v[48:49], v176 offset:30720
	ds_read_b64_tr_b16 v[50:51], v176 offset:31232
	v_mfma_f32_32x32x16_bf16 v[80:95], v[152:155], v[116:119], v[80:95]
	v_pk_add_f32 v[250:251], v[54:55], v[250:251]
	v_pk_add_f32 v[250:251], v[56:57], v[250:251]
	v_cvt_pk_bf16_f32 v134, v52, v53
	v_cvt_pk_bf16_f32 v135, v54, v55
	ds_read_b64_tr_b16 v[52:53], v176 offset:27648
	ds_read_b64_tr_b16 v[54:55], v176 offset:28160
	v_mfma_f32_32x32x16_bf16 v[96:111], v[148:151], v[112:115], v[96:111]
	v_pk_add_f32 v[250:251], v[58:59], v[250:251]
	s_nop 0
	v_pk_add_f32 v[250:251], v[60:61], v[250:251]
	s_nop 0
	v_cvt_pk_bf16_f32 v128, v56, v57
	v_cvt_pk_bf16_f32 v129, v58, v59
	ds_read_b64_tr_b16 v[56:57], v176 offset:31744
	ds_read_b64_tr_b16 v[58:59], v176 offset:32256
	v_mfma_f32_32x32x16_bf16 v[80:95], v[144:147], v[112:115], v[80:95]
	v_pk_add_f32 v[250:251], v[62:63], v[250:251]
	s_nop 0
	v_add_f32_e32 v72, v250, v251
	v_cvt_pk_bf16_f32 v130, v60, v61
	v_cvt_pk_bf16_f32 v131, v62, v63
	s_add_i32 s8, s50, 1
	s_cmp_ge_u32 s8, s4
	s_cselect_b64 s[46:47], -1, 0
	s_and_b64 vcc, exec, s[46:47]
	s_cbranch_vccnz .LBB0_1376
	s_add_i32 s8, s57, s5
	v_lshl_add_u64 v[60:61], v[202:203], 0, s[86:87]
	s_mov_b32 s9, m0
	s_mov_b32 m0, s8
	s_nop 0
	global_load_lds_dwordx4 v[60:61], off
	s_mov_b32 m0, s9

.LBB0_1383:
	ds_read_b128 v[2:5], v239 offset:256
	ds_read_b128 v[6:9], v239 offset:288
	ds_read_b128 v[10:13], v239 offset:320
	ds_read_b128 v[48:51], v239 offset:352
	ds_read_b128 v[176:179], v239 offset:384
	ds_read_b128 v[52:55], v239 offset:416
	ds_read_b128 v[56:59], v239 offset:448
	ds_read_b128 v[60:63], v239 offset:480
	s_waitcnt lgkmcnt(4)
	v_pk_add_f32 v[78:79], v[50:51], v[236:237] op_sel:[0,1] op_sel_hi:[1,1] neg_lo:[1,1] neg_hi:[1,1]
	v_pk_add_f32 v[76:77], v[48:49], v[236:237] op_sel:[0,1] op_sel_hi:[1,1] neg_lo:[1,1] neg_hi:[1,1]
	v_pk_add_f32 v[74:75], v[12:13], v[236:237] op_sel:[0,1] op_sel_hi:[1,1] neg_lo:[1,1] neg_hi:[1,1]
	v_pk_add_f32 v[72:73], v[10:11], v[236:237] op_sel:[0,1] op_sel_hi:[1,1] neg_lo:[1,1] neg_hi:[1,1]
	v_pk_add_f32 v[70:71], v[8:9], v[236:237] op_sel:[0,1] op_sel_hi:[1,1] neg_lo:[1,1] neg_hi:[1,1]
	v_pk_add_f32 v[68:69], v[6:7], v[236:237] op_sel:[0,1] op_sel_hi:[1,1] neg_lo:[1,1] neg_hi:[1,1]
	v_pk_add_f32 v[66:67], v[4:5], v[236:237] op_sel:[0,1] op_sel_hi:[1,1] neg_lo:[1,1] neg_hi:[1,1]
	v_pk_add_f32 v[64:65], v[2:3], v[236:237] op_sel:[0,1] op_sel_hi:[1,1] neg_lo:[1,1] neg_hi:[1,1]
	s_waitcnt lgkmcnt(0)
	v_pk_add_f32 v[62:63], v[62:63], v[236:237] op_sel:[0,1] op_sel_hi:[1,1] neg_lo:[1,1] neg_hi:[1,1]
	v_pk_add_f32 v[60:61], v[60:61], v[236:237] op_sel:[0,1] op_sel_hi:[1,1] neg_lo:[1,1] neg_hi:[1,1]
	v_pk_add_f32 v[58:59], v[58:59], v[236:237] op_sel:[0,1] op_sel_hi:[1,1] neg_lo:[1,1] neg_hi:[1,1]
	v_pk_add_f32 v[56:57], v[56:57], v[236:237] op_sel:[0,1] op_sel_hi:[1,1] neg_lo:[1,1] neg_hi:[1,1]
	v_pk_add_f32 v[54:55], v[54:55], v[236:237] op_sel:[0,1] op_sel_hi:[1,1] neg_lo:[1,1] neg_hi:[1,1]
	v_pk_add_f32 v[52:53], v[52:53], v[236:237] op_sel:[0,1] op_sel_hi:[1,1] neg_lo:[1,1] neg_hi:[1,1]
	v_pk_add_f32 v[50:51], v[178:179], v[236:237] op_sel:[0,1] op_sel_hi:[1,1] neg_lo:[1,1] neg_hi:[1,1]
	v_pk_add_f32 v[48:49], v[176:177], v[236:237] op_sel:[0,1] op_sel_hi:[1,1] neg_lo:[1,1] neg_hi:[1,1]
	v_add_u32_e32 v4, s57, v236
	ds_read_b64_tr_b16 v[184:185], v4 offset:24576
	ds_read_b64_tr_b16 v[186:187], v4 offset:25088
	v_mfma_f32_32x32x16_bf16 v[64:79], v[172:175], v[124:127], v[64:79]
	v_pk_add_f32 v[244:245], v[96:97], v[98:99]
	v_pk_add_f32 v[244:245], v[100:101], v[244:245]
	v_cvt_pk_bf16_f32 v140, v96, v97
	v_cvt_pk_bf16_f32 v141, v98, v99
	ds_read_b64_tr_b16 v[180:181], v4 offset:28672
	ds_read_b64_tr_b16 v[182:183], v4 offset:29184
	v_mfma_f32_32x32x16_bf16 v[48:63], v[168:171], v[124:127], v[48:63]
	v_pk_add_f32 v[244:245], v[102:103], v[244:245]
	v_pk_add_f32 v[244:245], v[104:105], v[244:245]
	v_cvt_pk_bf16_f32 v142, v100, v101
	v_cvt_pk_bf16_f32 v143, v102, v103
	ds_read_b64_tr_b16 v[176:177], v4 offset:25600
	ds_read_b64_tr_b16 v[178:179], v4 offset:26112
	v_mfma_f32_32x32x16_bf16 v[64:79], v[164:167], v[120:123], v[64:79]
	v_pk_add_f32 v[244:245], v[106:107], v[244:245]
	v_pk_add_f32 v[244:245], v[108:109], v[244:245]
	v_cvt_pk_bf16_f32 v136, v104, v105
	v_cvt_pk_bf16_f32 v137, v106, v107
	ds_read_b64_tr_b16 v[100:101], v4 offset:29696
	ds_read_b64_tr_b16 v[102:103], v4 offset:30208
	v_mfma_f32_32x32x16_bf16 v[48:63], v[160:163], v[120:123], v[48:63]
	v_pk_add_f32 v[244:245], v[110:111], v[244:245]
	v_pk_add_f32 v[244:245], v[80:81], v[244:245]
	v_cvt_pk_bf16_f32 v138, v108, v109
	v_cvt_pk_bf16_f32 v139, v110, v111
	ds_read_b64_tr_b16 v[96:97], v4 offset:26624
	ds_read_b64_tr_b16 v[98:99], v4 offset:27136
	v_mfma_f32_32x32x16_bf16 v[64:79], v[156:159], v[116:119], v[64:79]
	v_pk_add_f32 v[244:245], v[82:83], v[244:245]
	v_pk_add_f32 v[244:245], v[84:85], v[244:245]
	v_cvt_pk_bf16_f32 v132, v80, v81
	v_cvt_pk_bf16_f32 v133, v82, v83
	ds_read_b64_tr_b16 v[10:11], v4 offset:30720
	ds_read_b64_tr_b16 v[12:13], v4 offset:31232
	v_mfma_f32_32x32x16_bf16 v[48:63], v[152:155], v[116:119], v[48:63]
	v_pk_add_f32 v[244:245], v[86:87], v[244:245]
	v_pk_add_f32 v[244:245], v[88:89], v[244:245]
	v_cvt_pk_bf16_f32 v134, v84, v85
	v_cvt_pk_bf16_f32 v135, v86, v87
	ds_read_b64_tr_b16 v[6:7], v4 offset:27648
	ds_read_b64_tr_b16 v[8:9], v4 offset:28160
	v_mfma_f32_32x32x16_bf16 v[64:79], v[148:151], v[112:115], v[64:79]
	v_pk_add_f32 v[244:245], v[90:91], v[244:245]
	s_nop 0
	v_pk_add_f32 v[244:245], v[92:93], v[244:245]
	s_nop 0
	v_cvt_pk_bf16_f32 v128, v88, v89
	v_cvt_pk_bf16_f32 v129, v90, v91
	ds_read_b64_tr_b16 v[2:3], v4 offset:31744
	ds_read_b64_tr_b16 v[4:5], v4 offset:32256
	v_mfma_f32_32x32x16_bf16 v[48:63], v[144:147], v[112:115], v[48:63]
	v_pk_add_f32 v[244:245], v[94:95], v[244:245]
	s_nop 0
	v_add_f32_e32 v80, v244, v245
	v_cvt_pk_bf16_f32 v130, v92, v93
	v_cvt_pk_bf16_f32 v131, v94, v95
	s_add_i32 s61, s50, 2
	s_cmp_ge_u32 s61, s4
	s_cselect_b64 s[48:49], -1, 0
	s_and_b64 vcc, exec, s[48:49]
	s_cbranch_vccnz .LBB0_1385
	s_add_i32 s8, s58, s5
	s_mov_b32 s9, m0
	s_mov_b32 m0, s8
	s_nop 0
	global_load_lds_dwordx4 v[202:203], off
	s_mov_b32 m0, s9
